# attention phase: 96 packed fp32 VOP3P ops (v_pk_add/mul_f32) split into single ops beside the MFMAs (asm guide 7.5)
# baseline (speedup 1.0000x reference)
; DI void attn_phase(const Params& P, LAS unsigned char* lds, int layer) {
;     ...
;         if (mixB) { for (int i = tid; i < 257; i += NTHR) bt[i] = relb[hk * 257 + i] * LOG2E; }
.LBB0_1334:
	v_add_u32_e32 v4, s0, v0
	v_add_u32_e32 v6, s1, v1
	v_ashrrev_i32_e32 v5, 31, v4
	v_ashrrev_i32_e32 v7, 31, v6
	v_lshl_add_u64 v[4:5], v[4:5], 2, s[80:81]
	v_lshl_add_u64 v[6:7], v[6:7], 2, s[80:81]
	global_load_dword v4, v[4:5], off
	s_nop 0
	global_load_dword v5, v[6:7], off
	v_add_u32_e32 v2, -2, v2
	s_mov_b32 s2, 0x3fb8aa3b
	v_cmp_eq_u32_e32 vcc, 0, v2
	v_add_u32_e32 v1, 0x400, v1
	v_add_u32_e32 v0, 0x400, v0
	s_or_b64 s[24:25], vcc, s[24:25]
	s_waitcnt vmcnt(0)
	v_mul_f32_e32 v4, s2, v4
	v_mul_f32_e32 v5, s2, v5
	ds_write2st64_b32 v3, v4, v5 offset1:8
	v_add_u32_e32 v3, 0x1000, v3
	s_andn2_b64 exec, exec, s[24:25]
	s_cbranch_execnz .LBB0_1334
	s_or_b64 exec, exec, s[24:25]
	s_mov_b64 s[24:25], 0
	s_mov_b64 s[26:27], exec
	v_readlane_b32 s0, v235, 17
	v_readlane_b32 s1, v235, 18
	s_and_b64 s[0:1], s[26:27], s[0:1]
	s_mov_b64 exec, s[0:1]
	s_mov_b64 s[24:25], exec
	v_lshlrev_b32_e32 v1, 2, v197
	s_or_b64 exec, exec, s[26:27]
	s_orn2_b64 s[24:25], s[24:25], exec
	v_mov_b32_e32 v0, v197

; DI void attn_phase(const Params& P, LAS unsigned char* lds, int layer) {
;     ...
;             if (wave_on && j >= wlo && j <= whi) {
;                 const LAS unsigned char* Ks = lds + AT_KS + buf * 9216; const LAS unsigned char* Vt = lds + AT_VT + buf * 9216;
;                 f32x16 S0, S1; bf16x8 kf0[4], kf1[4];
; #pragma unroll
;                 for (int r = 0; r < 16; ++r) { S0[r] = 0.f; S1[r] = 0.f; }
; #pragma unroll
;                 for (int s = 0; s < 4; ++s) { kf0[s] = *(const LAS bf16x8*)(Ks + ql * 144 + 32 * s + 16 * h); kf1[s] = *(const LAS bf16x8*)(Ks + (32 + ql) * 144 + 32 * s + 16 * h); }
;                 __builtin_amdgcn_sched_barrier(0);
;                 __builtin_amdgcn_s_setprio(1);
; #pragma unroll
;                 for (int s = 0; s < 4; ++s) {
;                     S0 = __builtin_amdgcn_mfma_f32_32x32x16_bf16(kf0[s], qf[s], S0, 0, 0, 0);
;                     S1 = __builtin_amdgcn_mfma_f32_32x32x16_bf16(kf1[s], qf[s], S1, 0, 0, 0);
;                 }
;                 __builtin_amdgcn_s_setprio(0);
;                 bf16x8 vf0[4], vf1[4];
; #pragma unroll
;                 for (int kb = 0; kb < 2; ++kb)
; #pragma unroll
;                     for (int s = 0; s < 2; ++s) {
;                         const int kg = 8 * kb + 4 * s + h;
;                         const int ko = (kg ^ (ql >> 3)) << 3, ko2 = ((kg + 2) ^ (ql >> 3)) << 3;
;                         { const s16x4 lo = *(const LAS s16x4*)(Vt + ql * 144 + ko), hi = *(const LAS s16x4*)(Vt + ql * 144 + ko2);
;                           vf0[kb * 2 + s] = __builtin_shufflevector(lo, hi, 0, 1, 2, 3, 4, 5, 6, 7); }
;                         { const s16x4 lo = *(const LAS s16x4*)(Vt + (32 + ql) * 144 + (ko ^ 32)), hi = *(const LAS s16x4*)(Vt + (32 + ql) * 144 + (ko2 ^ 32));
;                           vf1[kb * 2 + s] = __builtin_shufflevector(lo, hi, 0, 1, 2, 3, 4, 5, 6, 7); }
;                     }
;                 __builtin_amdgcn_sched_barrier(0);
;                 if (mixB) {
;                     const int rel0 = 64 * (j - cw);
;                     if (rel0 <= -192) { const float bb = bt[0];
; #pragma unroll
;                         for (int r = 0; r < 16; ++r) { S0[r] += bb; S1[r] += bb; }
;                     } else if (rel0 >= -64) {
;                         const LAS float* bp = bt + (rel0 - (32 * (wid & 1) + ql) + 4 * h + 128);
; #pragma unroll
.LBB0_1378:
	s_and_b32 s18, s43, 1
	s_cmp_lt_u32 s68, s76
	s_cselect_b64 s[16:17], -1, 0
	s_cmp_gt_i32 s68, s93
	s_cselect_b64 s[24:25], -1, 0
	s_or_b64 s[16:17], s[16:17], s[24:25]
	s_and_b64 vcc, exec, s[16:17]
	s_cbranch_vccnz .LBB0_1390
	s_mul_i32 s1, s18, 0x2400
	v_add_u32_e32 v88, s1, v182
	v_add_u32_e32 v40, v88, v183
	ds_read_b128 v[32:35], v40
	ds_read_b128 v[64:67], v40 offset:32
	ds_read_b128 v[36:39], v40 offset:4608
	ds_read_b128 v[68:71], v40 offset:4640
	ds_read_b128 v[72:75], v40 offset:64
	ds_read_b128 v[76:79], v40 offset:96
	ds_read_b128 v[80:83], v40 offset:4672
	ds_read_b128 v[84:87], v40 offset:4704
	s_setprio 1
	s_setprio 0
	s_waitcnt lgkmcnt(7)
	v_mfma_f32_32x32x16_bf16 v[48:63], v[32:35], v[104:107], 0
	s_waitcnt lgkmcnt(5)
	v_mfma_f32_32x32x16_bf16 v[32:47], v[36:39], v[104:107], 0
	v_mfma_f32_32x32x16_bf16 v[48:63], v[64:67], v[108:111], v[48:63]
	v_add_u32_e32 v64, v88, v184
	v_add_u32_e32 v65, v88, v185
	ds_read_b64 v[156:157], v64 offset:18432
	ds_read_b64 v[158:159], v65 offset:18432
	ds_read_b64 v[162:163], v65 offset:23072
	ds_read_b64 v[160:161], v64 offset:23072
	v_add_u32_e32 v64, v88, v186
	v_add_u32_e32 v65, v88, v187
	v_add_u32_e32 v66, v88, v188
	v_add_u32_e32 v67, v88, v189
	s_waitcnt lgkmcnt(8)
	v_mfma_f32_32x32x16_bf16 v[32:47], v[68:71], v[108:111], v[32:47]
	ds_read_b64 v[148:149], v64 offset:18432
	ds_read_b64 v[150:151], v65 offset:18432
	ds_read_b64 v[152:153], v66 offset:23040
	ds_read_b64 v[154:155], v67 offset:23040
	v_add_u32_e32 v64, v88, v190
	v_add_u32_e32 v65, v88, v191
	ds_read_b64 v[140:141], v64 offset:18432
	ds_read_b64 v[142:143], v65 offset:18432
	ds_read_b64 v[146:147], v65 offset:23072
	ds_read_b64 v[144:145], v64 offset:23072
	v_add_u32_e32 v64, v88, v192
	v_add_u32_e32 v65, v88, v193
	v_add_u32_e32 v66, v88, v194
	s_waitcnt lgkmcnt(14)
	v_mfma_f32_32x32x16_bf16 v[48:63], v[72:75], v[112:115], v[48:63]
	v_add_u32_e32 v67, v88, v195
	ds_read_b64 v[132:133], v64 offset:18432
	ds_read_b64 v[134:135], v65 offset:18432
	ds_read_b64 v[136:137], v66 offset:23040
	ds_read_b64 v[138:139], v67 offset:23040
	s_waitcnt lgkmcnt(14)
	v_mfma_f32_32x32x16_bf16 v[32:47], v[80:83], v[112:115], v[32:47]
	v_mfma_f32_32x32x16_bf16 v[48:63], v[76:79], v[100:103], v[48:63]
	v_mfma_f32_32x32x16_bf16 v[32:47], v[84:87], v[100:103], v[32:47]
	s_and_b64 vcc, exec, s[44:45]
	s_cbranch_vccnz .LBB0_1389
	s_add_i32 s1, s77, s68
	s_cmp_gt_i32 s1, -3
	s_mov_b64 s[16:17], -1
	s_cbranch_scc0 .LBB0_1386
	s_cmp_eq_u32 s1, -2
	s_cbranch_scc1 .LBB0_1383
	ds_read2_b32 v[64:65], v204 offset1:1
	ds_read2_b32 v[66:67], v204 offset0:2 offset1:3
	ds_read2_b32 v[68:69], v204 offset0:8 offset1:9
	ds_read2_b32 v[70:71], v204 offset0:10 offset1:11
	ds_read2_b32 v[72:73], v204 offset0:16 offset1:17
	ds_read2_b32 v[74:75], v204 offset0:18 offset1:19
	ds_read2_b32 v[76:77], v204 offset0:24 offset1:25
	ds_read2_b32 v[78:79], v204 offset0:26 offset1:27
	ds_read2_b32 v[80:81], v204 offset0:32 offset1:33
	ds_read2_b32 v[82:83], v204 offset0:34 offset1:35
	ds_read2_b32 v[84:85], v204 offset0:40 offset1:41
	ds_read2_b32 v[86:87], v204 offset0:42 offset1:43
	ds_read2_b32 v[88:89], v204 offset0:48 offset1:49
	ds_read2_b32 v[90:91], v204 offset0:50 offset1:51
	ds_read2_b32 v[92:93], v204 offset0:56 offset1:57
	ds_read2_b32 v[94:95], v204 offset0:58 offset1:59
	s_waitcnt lgkmcnt(14)
	v_add_f32_e32 v64, v48, v64
	v_add_f32_e32 v65, v49, v65
	s_waitcnt lgkmcnt(8)
	v_add_f32_e32 v78, v62, v78
	v_add_f32_e32 v79, v63, v79
	v_add_f32_e32 v76, v60, v76
	v_add_f32_e32 v77, v61, v77
	v_add_f32_e32 v74, v58, v74
	v_add_f32_e32 v75, v59, v75
	v_add_f32_e32 v72, v56, v72
	v_add_f32_e32 v73, v57, v73
	v_add_f32_e32 v70, v54, v70
	v_add_f32_e32 v71, v55, v71
	v_add_f32_e32 v68, v52, v68
	v_add_f32_e32 v69, v53, v69
	v_add_f32_e32 v66, v50, v66
	v_add_f32_e32 v67, v51, v67
	s_waitcnt lgkmcnt(7)
	v_add_f32_e32 v80, v32, v80
	v_add_f32_e32 v81, v33, v81
	s_waitcnt lgkmcnt(0)
	v_add_f32_e32 v94, v46, v94
	v_add_f32_e32 v95, v47, v95
	v_add_f32_e32 v92, v44, v92
	v_add_f32_e32 v93, v45, v93
	v_add_f32_e32 v90, v42, v90
	v_add_f32_e32 v91, v43, v91
	v_add_f32_e32 v88, v40, v88
	v_add_f32_e32 v89, v41, v89
	v_add_f32_e32 v86, v38, v86
	v_add_f32_e32 v87, v39, v87
	v_add_f32_e32 v84, v36, v84
	v_add_f32_e32 v85, v37, v85
	v_add_f32_e32 v82, v34, v82
	v_add_f32_e32 v83, v35, v83
	s_mov_b64 s[16:17], 0
; DI void attn_phase(const Params& P, LAS unsigned char* lds, int layer) {
;     ...
;                     } else {
;                         const int base = rel0 - (32 * (wid & 1) + ql) + 4 * h + 128;
; #pragma unroll
;                         for (int r = 0; r < 16; ++r) { const int kk = (r & 3) + 8 * (r >> 2);
;                             int i0 = base + kk, i1 = base + 32 + kk; i0 = i0 < 0 ? 0 : (i0 > 256 ? 256 : i0); i1 = i1 < 0 ? 0 : (i1 > 256 ? 256 : i1);
;                             S0[r] += bt[i0]; S1[r] += bt[i1]; }
;                     }
.LBB0_1383:
	s_andn2_b64 vcc, exec, s[16:17]
	s_cbranch_vccnz .LBB0_1385
	v_max_i32_e32 v64, 0xffffff80, v203
	v_max_i32_e32 v65, 0xffffff60, v203
	v_max_i32_e32 v66, 0xffffff7f, v203
	v_max_i32_e32 v67, 0xffffff5f, v203
	v_max_i32_e32 v68, 0xffffff7e, v203
	v_max_i32_e32 v69, 0xffffff5e, v203
	v_max_i32_e32 v70, 0xffffff7d, v203
	v_max_i32_e32 v71, 0xffffff5d, v203
	v_lshl_add_u32 v64, v64, 2, 0
	v_lshl_add_u32 v65, v65, 2, 0
	v_lshl_add_u32 v66, v66, 2, 0
	v_lshl_add_u32 v67, v67, 2, 0
	v_lshl_add_u32 v68, v68, 2, 0
	v_lshl_add_u32 v69, v69, 2, 0
	v_lshl_add_u32 v70, v70, 2, 0
	v_lshl_add_u32 v71, v71, 2, 0
	ds_read_b32 v64, v64 offset:37376
	ds_read_b32 v80, v65 offset:37504
	ds_read_b32 v65, v66 offset:37380
	ds_read_b32 v81, v67 offset:37508
	ds_read_b32 v66, v68 offset:37384
	ds_read_b32 v82, v69 offset:37512
	ds_read_b32 v67, v70 offset:37388
	ds_read_b32 v83, v71 offset:37516
	v_max_i32_e32 v68, 0xffffff78, v203
	v_max_i32_e32 v69, 0xffffff58, v203
	v_max_i32_e32 v70, 0xffffff77, v203
	v_max_i32_e32 v71, 0xffffff57, v203
	v_max_i32_e32 v72, 0xffffff76, v203
	v_max_i32_e32 v73, 0xffffff56, v203
	v_max_i32_e32 v74, 0xffffff75, v203
	v_max_i32_e32 v75, 0xffffff55, v203
	v_lshl_add_u32 v68, v68, 2, 0
	v_lshl_add_u32 v69, v69, 2, 0
	v_lshl_add_u32 v70, v70, 2, 0
	v_lshl_add_u32 v71, v71, 2, 0
	v_lshl_add_u32 v72, v72, 2, 0
	v_lshl_add_u32 v73, v73, 2, 0
	v_lshl_add_u32 v74, v74, 2, 0
	v_lshl_add_u32 v75, v75, 2, 0
	ds_read_b32 v68, v68 offset:37408
	ds_read_b32 v84, v69 offset:37536
	ds_read_b32 v69, v70 offset:37412
	ds_read_b32 v85, v71 offset:37540
	ds_read_b32 v70, v72 offset:37416
	ds_read_b32 v86, v73 offset:37544
	ds_read_b32 v71, v74 offset:37420
	ds_read_b32 v87, v75 offset:37548
	v_max_i32_e32 v72, 0xffffff70, v203
	v_max_i32_e32 v73, 0xffffff50, v203
	v_max_i32_e32 v74, 0xffffff6f, v203
	v_max_i32_e32 v75, 0xffffff4f, v203
	v_max_i32_e32 v79, 0xffffff4d, v203
	v_lshl_add_u32 v72, v72, 2, 0
	v_lshl_add_u32 v73, v73, 2, 0
	v_lshl_add_u32 v74, v74, 2, 0
	v_lshl_add_u32 v75, v75, 2, 0
	v_max_i32_e32 v76, 0xffffff6e, v203
	v_max_i32_e32 v77, 0xffffff4e, v203
	v_max_i32_e32 v78, 0xffffff6d, v203
	v_lshl_add_u32 v79, v79, 2, 0
	v_lshl_add_u32 v76, v76, 2, 0
	v_lshl_add_u32 v77, v77, 2, 0
	v_lshl_add_u32 v78, v78, 2, 0
	ds_read_b32 v72, v72 offset:37440
	ds_read_b32 v88, v73 offset:37568
	ds_read_b32 v73, v74 offset:37444
	ds_read_b32 v89, v75 offset:37572
	ds_read_b32 v74, v76 offset:37448
	ds_read_b32 v90, v77 offset:37576
	ds_read_b32 v75, v78 offset:37452
	ds_read_b32 v91, v79 offset:37580
	v_max_i32_e32 v79, 0xffffff47, v203
	v_max_i32_e32 v78, 0xffffff67, v203
	v_lshl_add_u32 v96, v79, 2, 0
	v_max_i32_e32 v79, 0xffffff46, v203
	v_max_i32_e32 v76, 0xffffff68, v203
	v_max_i32_e32 v77, 0xffffff48, v203
	v_lshl_add_u32 v93, v78, 2, 0
	v_max_i32_e32 v78, 0xffffff66, v203
	v_lshl_add_u32 v94, v79, 2, 0
	v_max_i32_e32 v79, 0xffffff65, v203
	v_max_i32_e32 v92, 0xffffff45, v203
	v_lshl_add_u32 v76, v76, 2, 0
	v_lshl_add_u32 v77, v77, 2, 0
	v_lshl_add_u32 v78, v78, 2, 0
	v_lshl_add_u32 v79, v79, 2, 0
	v_lshl_add_u32 v95, v92, 2, 0
	ds_read_b32 v76, v76 offset:37472
	ds_read_b32 v92, v77 offset:37600
	ds_read_b32 v78, v78 offset:37480
	ds_read_b32 v79, v79 offset:37484
	ds_read_b32 v77, v93 offset:37476
	ds_read_b32 v95, v95 offset:37612
	ds_read_b32 v94, v94 offset:37608
	ds_read_b32 v93, v96 offset:37604
	s_waitcnt lgkmcnt(4)
	v_add_f32_e32 v78, v62, v78
	v_add_f32_e32 v79, v63, v79
	s_waitcnt lgkmcnt(3)
	v_add_f32_e32 v76, v60, v76
	v_add_f32_e32 v77, v61, v77
	v_add_f32_e32 v74, v58, v74
	v_add_f32_e32 v75, v59, v75
	v_add_f32_e32 v72, v56, v72
	v_add_f32_e32 v73, v57, v73
	v_add_f32_e32 v70, v54, v70
	v_add_f32_e32 v71, v55, v71
	v_add_f32_e32 v68, v52, v68
	v_add_f32_e32 v69, v53, v69
	v_add_f32_e32 v66, v50, v66
	v_add_f32_e32 v67, v51, v67
	v_add_f32_e32 v64, v48, v64
	v_add_f32_e32 v65, v49, v65
	s_waitcnt lgkmcnt(1)
	v_add_f32_e32 v94, v46, v94
	v_add_f32_e32 v95, v47, v95
	s_waitcnt lgkmcnt(0)
	v_add_f32_e32 v92, v44, v92
	v_add_f32_e32 v93, v45, v93
	v_add_f32_e32 v90, v42, v90
	v_add_f32_e32 v91, v43, v91
	v_add_f32_e32 v88, v40, v88
	v_add_f32_e32 v89, v41, v89
	v_add_f32_e32 v86, v38, v86
	v_add_f32_e32 v87, v39, v87
	v_add_f32_e32 v84, v36, v84
	v_add_f32_e32 v85, v37, v85
	v_add_f32_e32 v82, v34, v82
	v_add_f32_e32 v83, v35, v83
	v_add_f32_e32 v80, v32, v80
	v_add_f32_e32 v81, v33, v81

; DI void attn_phase(const Params& P, LAS unsigned char* lds, int layer) {
;     ...
;                     if (rel0 <= -192) { const float bb = bt[0];
; #pragma unroll
;                         for (int r = 0; r < 16; ++r) { S0[r] += bb; S1[r] += bb; }
.LBB0_1386:
	s_andn2_b64 vcc, exec, s[16:17]
	s_cbranch_vccnz .LBB0_1388
	ds_read_b32 v80, v97 offset:36864
	s_waitcnt lgkmcnt(0)
	s_nop 0
	v_add_f32_e32 v78, v62, v80
	v_add_f32_e32 v79, v63, v80
	v_add_f32_e32 v76, v60, v80
	v_add_f32_e32 v77, v61, v80
	v_add_f32_e32 v74, v58, v80
	v_add_f32_e32 v75, v59, v80
	v_add_f32_e32 v72, v56, v80
	v_add_f32_e32 v73, v57, v80
	v_add_f32_e32 v70, v54, v80
	v_add_f32_e32 v71, v55, v80
	v_add_f32_e32 v68, v52, v80
	v_add_f32_e32 v69, v53, v80
	v_add_f32_e32 v66, v50, v80
	v_add_f32_e32 v67, v51, v80
	v_add_f32_e32 v64, v48, v80
	v_add_f32_e32 v65, v49, v80
	v_add_f32_e32 v94, v46, v80
	v_add_f32_e32 v95, v47, v80
	v_add_f32_e32 v92, v44, v80
	v_add_f32_e32 v93, v45, v80
	v_add_f32_e32 v90, v42, v80
	v_add_f32_e32 v91, v43, v80
	v_add_f32_e32 v88, v40, v80
	v_add_f32_e32 v89, v41, v80
	v_add_f32_e32 v86, v38, v80
	v_add_f32_e32 v87, v39, v80
	v_add_f32_e32 v84, v36, v80
	v_add_f32_e32 v85, v37, v80
	v_add_f32_e32 v82, v34, v80
	v_add_f32_e32 v83, v35, v80
	v_add_f32_e32 v81, v33, v80
	v_add_f32_e32 v80, v32, v80

; DI unsigned pk2(float lo, float hi) { f32x2 v = {lo, hi}; hbf2 r = __builtin_convertvector(v, hbf2); return __builtin_bit_cast(unsigned, r); }
; DI float fast_exp2(float x) { return __builtin_amdgcn_exp2f(x); }
; DI void attn_phase(const Params& P, LAS unsigned char* lds, int layer) {
;     ...
;                 float mx = S0[0];
; #pragma unroll
;                 for (int r = 1; r < 16; ++r) mx = fmaxf(mx, S0[r]);
; #pragma unroll
;                 for (int r = 0; r < 16; ++r) mx = fmaxf(mx, S1[r]);
;                 mx = fmaxf(mx, __shfl_xor(mx, 32));
;                 const float mn = fmaxf(m_run, mx); const float alpha = fast_exp2(m_run - mn); m_run = mn;
;                 float ps = 0.f;
; #pragma unroll
;                 for (int r = 0; r < 16; ++r) { S0[r] = fast_exp2(S0[r] - mn); S1[r] = fast_exp2(S1[r] - mn); ps += S0[r] + S1[r]; }
;                 l_run = l_run * alpha + ps;
; #pragma unroll
;                 for (int r = 0; r < 16; ++r) { O0[r] *= alpha; O1[r] *= alpha; }
; #pragma unroll
;                 for (int kb = 0; kb < 2; ++kb)
; #pragma unroll
;                     for (int s = 0; s < 2; ++s) {
;                         u32x4 pw;
; #pragma unroll
;                         for (int q = 0; q < 4; ++q) pw[q] = kb == 0 ? pk2(S0[8 * s + 2 * q], S0[8 * s + 2 * q + 1]) : pk2(S1[8 * s + 2 * q], S1[8 * s + 2 * q + 1]);
;                         const bf16x8 pf = __builtin_bit_cast(bf16x8, pw);
;                         __builtin_amdgcn_s_setprio(1);
;                         O0 = __builtin_amdgcn_mfma_f32_32x32x16_bf16(vf0[kb * 2 + s], pf, O0, 0, 0, 0);
;                         O1 = __builtin_amdgcn_mfma_f32_32x32x16_bf16(vf1[kb * 2 + s], pf, O1, 0, 0, 0);
;                         __builtin_amdgcn_s_setprio(0);
;                     }
.LBB0_1389:
	s_nop 8
	v_max_f32_e32 v64, v49, v49
	v_max_f32_e32 v65, v48, v48
	v_max_f32_e32 v64, v65, v64
	v_max3_f32 v64, v64, v50, v51
	v_max3_f32 v64, v64, v52, v53
	v_max3_f32 v64, v64, v54, v55
	v_max3_f32 v64, v64, v56, v57
	v_max3_f32 v64, v64, v58, v59
	v_max3_f32 v64, v64, v60, v61
	v_max3_f32 v64, v64, v62, v63
	v_max3_f32 v64, v64, v32, v33
	v_max3_f32 v64, v64, v34, v35
	v_max3_f32 v64, v64, v36, v37
	v_max3_f32 v64, v64, v38, v39
	v_and_b32_e32 v66, 64, v229
	v_max3_f32 v64, v64, v40, v41
	v_xor_b32_e32 v65, 32, v229
	v_add_u32_e32 v66, 64, v66
	v_max3_f32 v64, v64, v42, v43
	v_cmp_lt_i32_e32 vcc, v65, v66
	v_max3_f32 v64, v64, v44, v45
	v_max3_f32 v64, v64, v46, v47
	v_cndmask_b32_e32 v65, v229, v65, vcc
	v_lshlrev_b32_e32 v65, 2, v65
	ds_bpermute_b32 v65, v65, v64
	s_waitcnt lgkmcnt(0)
	v_max3_f32 v66, v205, v64, v65
	v_sub_f32_e32 v34, v34, v66
	v_sub_f32_e32 v48, v48, v66
	v_exp_f32_e32 v70, v34
	v_sub_f32_e32 v33, v33, v66
	v_sub_f32_e32 v34, v52, v66
	v_exp_f32_e32 v67, v48
	v_sub_f32_e32 v48, v49, v66
	v_exp_f32_e32 v96, v33
	v_sub_f32_e32 v33, v51, v66
	v_exp_f32_e32 v71, v34
	v_sub_f32_e32 v34, v36, v66
	v_exp_f32_e32 v64, v48
	v_exp_f32_e32 v72, v34
	v_exp_f32_e32 v48, v33
	v_sub_f32_e32 v33, v35, v66
	v_sub_f32_e32 v34, v54, v66
	v_exp_f32_e32 v36, v33
	v_sub_f32_e32 v33, v53, v66
	v_exp_f32_e32 v73, v34
	v_sub_f32_e32 v34, v38, v66
	v_exp_f32_e32 v74, v34
	v_exp_f32_e32 v34, v33
	v_sub_f32_e32 v33, v37, v66
	v_exp_f32_e32 v38, v33
	v_sub_f32_e32 v33, v55, v66
	v_sub_f32_e32 v49, v50, v66
	v_sub_f32_e32 v37, v56, v66
	v_exp_f32_e32 v50, v33
	v_sub_f32_e32 v33, v39, v66
	v_exp_f32_e32 v75, v37
	v_sub_f32_e32 v37, v40, v66
	v_exp_f32_e32 v40, v33
	v_sub_f32_e32 v33, v57, v66
	v_sub_f32_e32 v32, v32, v66
	v_exp_f32_e32 v76, v37
	v_sub_f32_e32 v37, v58, v66
	v_exp_f32_e32 v52, v33
	v_sub_f32_e32 v33, v41, v66
	v_exp_f32_e32 v68, v32
	v_exp_f32_e32 v77, v37
	v_sub_f32_e32 v37, v42, v66
	v_exp_f32_e32 v42, v33
	v_sub_f32_e32 v33, v59, v66
	v_exp_f32_e32 v78, v37
	v_sub_f32_e32 v37, v60, v66
	v_exp_f32_e32 v54, v33
	v_sub_f32_e32 v33, v43, v66
	v_exp_f32_e32 v79, v37
	v_sub_f32_e32 v37, v44, v66
	v_exp_f32_e32 v44, v33
	v_sub_f32_e32 v33, v61, v66
	v_sub_f32_e32 v32, v205, v66
	v_exp_f32_e32 v69, v49
	v_exp_f32_e32 v80, v37
	v_sub_f32_e32 v37, v62, v66
	v_exp_f32_e32 v56, v33
	v_sub_f32_e32 v33, v45, v66
	v_add_f32_e32 v65, v67, v68
	v_exp_f32_e32 v61, v37
	v_sub_f32_e32 v37, v46, v66
	v_exp_f32_e32 v46, v33
	v_sub_f32_e32 v33, v63, v66
	v_exp_f32_e32 v60, v32
	v_sub_f32_e32 v32, v47, v66
	v_exp_f32_e32 v58, v33
	v_exp_f32_e32 v62, v32
	v_add_f32_e32 v32, v64, v96
	v_add_f32_e32 v33, v65, v97
	v_add_f32_e32 v49, v69, v70
	v_add_f32_e32 v33, v32, v33
	v_add_f32_e32 v32, v32, v32
	v_exp_f32_e32 v81, v37
	v_mov_b32_e32 v37, v33
	v_add_f32_e32 v32, v48, v36
	v_add_f32_e32 v33, v49, v37
	v_add_f32_e32 v35, v71, v72
	v_add_f32_e32 v33, v32, v33
	v_add_f32_e32 v32, v32, v32
	v_mov_b32_e32 v39, v33
	v_add_f32_e32 v32, v34, v38
	v_add_f32_e32 v33, v35, v39
	v_add_f32_e32 v51, v73, v74
	v_add_f32_e32 v33, v32, v33
	v_add_f32_e32 v32, v32, v32
	v_mov_b32_e32 v41, v33
	v_add_f32_e32 v32, v50, v40
	v_add_f32_e32 v33, v51, v41
	v_add_f32_e32 v53, v75, v76
	v_add_f32_e32 v33, v32, v33
	v_add_f32_e32 v32, v32, v32
	v_mov_b32_e32 v43, v33
	v_add_f32_e32 v32, v52, v42
	v_add_f32_e32 v33, v53, v43
	v_add_f32_e32 v55, v77, v78
	v_add_f32_e32 v33, v32, v33
	v_add_f32_e32 v32, v32, v32
	v_mov_b32_e32 v45, v33
	v_add_f32_e32 v32, v54, v44
	v_add_f32_e32 v33, v55, v45
	v_add_f32_e32 v57, v79, v80
	v_add_f32_e32 v33, v32, v33
	v_add_f32_e32 v32, v32, v32
	v_mov_b32_e32 v47, v33
	v_add_f32_e32 v32, v56, v46
	v_add_f32_e32 v33, v57, v47
	v_add_f32_e32 v59, v61, v81
	v_add_f32_e32 v33, v32, v33
	v_add_f32_e32 v32, v32, v32
	v_mov_b32_e32 v63, v33
	v_mul_f32_e32 v14, v14, v60
	v_mul_f32_e32 v15, v15, v60
	v_mul_f32_e32 v12, v12, v60
	v_mul_f32_e32 v13, v13, v60
	v_mul_f32_e32 v10, v10, v60
	v_mul_f32_e32 v11, v11, v60
	v_mul_f32_e32 v8, v8, v60
	v_mul_f32_e32 v9, v9, v60
	v_mul_f32_e32 v6, v6, v60
	v_mul_f32_e32 v7, v7, v60
	v_mul_f32_e32 v4, v4, v60
	v_mul_f32_e32 v5, v5, v60
	v_mul_f32_e32 v2, v2, v60
	v_mul_f32_e32 v3, v3, v60
	v_mul_f32_e32 v0, v0, v60
	v_mul_f32_e32 v1, v1, v60
	v_mul_f32_e32 v30, v30, v60
	v_mul_f32_e32 v31, v31, v60
	v_mul_f32_e32 v28, v28, v60
	v_mul_f32_e32 v29, v29, v60
	v_mul_f32_e32 v26, v26, v60
	v_mul_f32_e32 v27, v27, v60
	v_mul_f32_e32 v24, v24, v60
	v_mul_f32_e32 v25, v25, v60
	v_mul_f32_e32 v22, v22, v60
	v_mul_f32_e32 v23, v23, v60
	v_mul_f32_e32 v20, v20, v60
	v_mul_f32_e32 v21, v21, v60
	v_mul_f32_e32 v18, v18, v60
	v_mul_f32_e32 v19, v19, v60
	v_mul_f32_e32 v16, v16, v60
	v_mul_f32_e32 v17, v17, v60
	v_add_f32_e32 v32, v58, v62
	v_add_f32_e32 v33, v59, v63
	v_cvt_pk_bf16_f32 v34, v71, v34
	v_add_f32_e32 v37, v32, v33
	v_cvt_pk_bf16_f32 v32, v67, v64
	v_cvt_pk_bf16_f32 v33, v69, v48
	v_cvt_pk_bf16_f32 v35, v73, v50
	s_setprio 1
	s_nop 0
	v_mfma_f32_32x32x16_bf16 v[0:15], v[156:159], v[32:35], v[0:15]
	v_mfma_f32_32x32x16_bf16 v[16:31], v[160:163], v[32:35], v[16:31]
	s_setprio 0
	v_cvt_pk_bf16_f32 v32, v75, v52
	v_cvt_pk_bf16_f32 v33, v77, v54
	v_cvt_pk_bf16_f32 v34, v79, v56
	v_cvt_pk_bf16_f32 v35, v61, v58
	s_setprio 1
	s_nop 0
	v_mfma_f32_32x32x16_bf16 v[0:15], v[148:151], v[32:35], v[0:15]
	v_mfma_f32_32x32x16_bf16 v[16:31], v[152:155], v[32:35], v[16:31]
	s_setprio 0
	v_cvt_pk_bf16_f32 v32, v68, v96
	v_cvt_pk_bf16_f32 v33, v70, v36
	v_cvt_pk_bf16_f32 v34, v72, v38
	v_cvt_pk_bf16_f32 v35, v74, v40
	s_setprio 1
	s_nop 0
	v_mfma_f32_32x32x16_bf16 v[0:15], v[140:143], v[32:35], v[0:15]
	v_mfma_f32_32x32x16_bf16 v[16:31], v[144:147], v[32:35], v[16:31]
	s_setprio 0
	v_cvt_pk_bf16_f32 v32, v76, v42
	v_cvt_pk_bf16_f32 v33, v78, v44
	v_cvt_pk_bf16_f32 v34, v80, v46
	v_cvt_pk_bf16_f32 v35, v81, v62
	s_setprio 1
	s_nop 0
	v_mfma_f32_32x32x16_bf16 v[0:15], v[132:135], v[32:35], v[0:15]
	v_mfma_f32_32x32x16_bf16 v[16:31], v[136:139], v[32:35], v[16:31]
	s_setprio 0
	v_fmac_f32_e32 v37, v177, v60
	v_mov_b32_e32 v205, v66
	v_mov_b32_e32 v177, v37

; DI unsigned pk2(float lo, float hi) { f32x2 v = {lo, hi}; hbf2 r = __builtin_convertvector(v, hbf2); return __builtin_bit_cast(unsigned, r); }
; DI float fast_exp2(float x) { return __builtin_amdgcn_exp2f(x); }
; DI void attn_phase(const Params& P, LAS unsigned char* lds, int layer) {
;     ...
;         if (wave_on) {
;             float lt = l_run + __shfl_xor(l_run, 32);
;             if (!mixB) lt += fast_exp2(sinkv - m_run);
;             const float inv = 1.0f / lt;
;             bf16_t* yp = (mixB ? YB : YA) + (size_t)(qrow0 + ql) * 512 + hq * 64 + 4 * h;
; #pragma unroll
;             for (int g4 = 0; g4 < 4; ++g4) {
;                 u32x2 w0, w1;
;                 w0.x = pk2(O0[4 * g4] * inv, O0[4 * g4 + 1] * inv); w0.y = pk2(O0[4 * g4 + 2] * inv, O0[4 * g4 + 3] * inv);
;                 w1.x = pk2(O1[4 * g4] * inv, O1[4 * g4 + 1] * inv); w1.y = pk2(O1[4 * g4 + 2] * inv, O1[4 * g4 + 3] * inv);
;                 *(u32x2*)(yp + 8 * g4) = w0; *(u32x2*)(yp + 32 + 8 * g4) = w1;
;             }
.LBB0_1405:
	v_readlane_b32 s94, v246, 25
	s_and_b64 vcc, exec, s[12:13]
	v_readlane_b32 s76, v246, 24
	v_readlane_b32 s95, v246, 26
	s_mov_b32 s96, s48
	s_mov_b32 s93, s56
	v_readlane_b32 s97, v246, 27
	s_cbranch_vccz .LBB0_1302
	v_and_b32_e32 v33, 64, v229
	v_xor_b32_e32 v32, 32, v229
	v_add_u32_e32 v33, 64, v33
	v_cmp_lt_i32_e32 vcc, v32, v33
	v_sub_f32_e32 v33, v175, v205
	v_exp_f32_e32 v33, v33
	v_cndmask_b32_e32 v32, v229, v32, vcc
	v_lshlrev_b32_e32 v32, 2, v32
	ds_bpermute_b32 v32, v32, v177
	s_and_b64 s[0:1], s[8:9], exec
	s_waitcnt lgkmcnt(0)
	v_add_f32_e32 v32, v177, v32
	v_add_f32_e32 v33, v33, v32
	v_cndmask_b32_e64 v32, v32, v33, s[8:9]
	v_div_scale_f32 v33, s[0:1], v32, v32, 1.0
	v_rcp_f32_e32 v34, v33
	s_mov_b32 s0, 0x5b00000
	s_cselect_b32 s0, s0, 0x7d00000
	s_add_u32 s0, s84, s0
	v_fma_f32 v35, -v33, v34, 1.0
	v_fmac_f32_e32 v34, v35, v34
	v_div_scale_f32 v35, vcc, 1.0, v32, 1.0
	v_mul_f32_e32 v36, v35, v34
	v_fma_f32 v37, -v33, v36, v35
	v_fmac_f32_e32 v36, v37, v34
	v_fma_f32 v33, -v33, v36, v35
	v_div_fmas_f32 v33, v33, v34, v36
	v_div_fixup_f32 v32, v33, v32, 1.0
	s_addc_u32 s1, s85, 0
	v_lshl_add_u64 v[34:35], v[178:179], 1, s[0:1]
	v_mul_f32_e32 v0, v0, v32
	v_mul_f32_e32 v1, v1, v32
	v_mul_f32_e32 v2, v2, v32
	v_mul_f32_e32 v3, v3, v32
	v_lshl_add_u64 v[34:35], s[10:11], 1, v[34:35]
	v_mov_b32_e32 v177, v97
	v_cvt_pk_bf16_f32 v0, v0, v1
	v_cvt_pk_bf16_f32 v1, v2, v3
	v_mul_f32_e32 v2, v16, v32
	v_mul_f32_e32 v3, v17, v32
	v_mul_f32_e32 v16, v18, v32
	v_mul_f32_e32 v17, v19, v32
	v_lshl_add_u64 v[34:35], v[34:35], 0, v[176:177]
	v_cvt_pk_bf16_f32 v2, v2, v3
	v_cvt_pk_bf16_f32 v3, v16, v17
	global_store_dwordx2 v[34:35], v[0:1], off
	global_store_dwordx2 v[34:35], v[2:3], off offset:64
	v_mul_f32_e32 v0, v4, v32
	v_mul_f32_e32 v1, v5, v32
	v_mul_f32_e32 v2, v6, v32
	v_mul_f32_e32 v3, v7, v32
	v_cvt_pk_bf16_f32 v0, v0, v1
	v_cvt_pk_bf16_f32 v1, v2, v3
	v_mul_f32_e32 v2, v20, v32
	v_mul_f32_e32 v3, v21, v32
	v_mul_f32_e32 v4, v22, v32
	v_mul_f32_e32 v5, v23, v32
	v_cvt_pk_bf16_f32 v2, v2, v3
	v_cvt_pk_bf16_f32 v3, v4, v5
	global_store_dwordx2 v[34:35], v[0:1], off offset:16
	global_store_dwordx2 v[34:35], v[2:3], off offset:80
	v_mul_f32_e32 v0, v8, v32
	v_mul_f32_e32 v1, v9, v32
	v_mul_f32_e32 v2, v10, v32
	v_mul_f32_e32 v3, v11, v32
	v_cvt_pk_bf16_f32 v0, v0, v1
	v_cvt_pk_bf16_f32 v1, v2, v3
	v_mul_f32_e32 v2, v24, v32
	v_mul_f32_e32 v3, v25, v32
	v_mul_f32_e32 v4, v26, v32
	v_mul_f32_e32 v5, v27, v32
	v_cvt_pk_bf16_f32 v2, v2, v3
	v_cvt_pk_bf16_f32 v3, v4, v5
	global_store_dwordx2 v[34:35], v[0:1], off offset:32
	global_store_dwordx2 v[34:35], v[2:3], off offset:96
	v_mul_f32_e32 v0, v12, v32
	v_mul_f32_e32 v1, v13, v32
	v_mul_f32_e32 v2, v14, v32
	v_mul_f32_e32 v3, v15, v32
	v_cvt_pk_bf16_f32 v0, v0, v1
	v_cvt_pk_bf16_f32 v1, v2, v3
	v_mul_f32_e32 v2, v28, v32
	v_mul_f32_e32 v3, v29, v32
	v_mul_f32_e32 v4, v30, v32
	v_mul_f32_e32 v5, v31, v32
	v_cvt_pk_bf16_f32 v2, v2, v3
	v_cvt_pk_bf16_f32 v3, v4, v5
	global_store_dwordx2 v[34:35], v[0:1], off offset:48
	global_store_dwordx2 v[34:35], v[2:3], off offset:112
	s_branch .LBB0_1302
